# XCD-local barrier fast path extended to 5 seams per layer (adds PB-PC and PD-PF)
# speedup vs baseline: 1.0223x; 1.0058x over previous
; __device__ __forceinline__ unsigned xb_ld(unsigned* p)              { return __hip_atomic_load(p, __ATOMIC_RELAXED, __HIP_MEMORY_SCOPE_AGENT); }
; __device__ __forceinline__ unsigned xb_add(unsigned* p, unsigned v) { return __hip_atomic_fetch_add(p, v, __ATOMIC_RELAXED, __HIP_MEMORY_SCOPE_AGENT); }
; #define XB_SPIN(cond, bar) do { unsigned _sp = 0; while (cond) { __builtin_amdgcn_s_sleep(1); \
;     if ((++_sp & 255u) == 0u) { if (xb_ld(&(bar)[XB_TMO])) break; if (_sp > XB_SPIN_CAP) { atomicAdd(&(bar)[XB_TMO], 1u); break; } } } } while (0)
; __device__ __forceinline__ void xcd_barrier(const XcdBarrier& b) {
;     asm volatile("s_waitcnt vmcnt(0)" ::: "memory");
;     __syncthreads();
;     if (threadIdx.x == 0) {
;         unsigned* bar = b.bar;
;         unsigned bx = (unsigned)__builtin_amdgcn_readfirstlane((int)b.x); asm volatile("" : "+s"(bx));
;         __builtin_amdgcn_s_waitcnt(0);
;         unsigned nloc = b.st[0], nx = b.st[1];
;         if (nloc == 0u) { xcd_barrier_complete(bar, bx, nloc, nx); b.st[0] = nloc; b.st[1] = nx; }
;         const unsigned old = xb_add(&bar[XB_XSUB(bx)], 1u);
;         const unsigned gen = old / nloc;
;         if (old + 1u == (gen + 1u) * nloc) {
;             __builtin_amdgcn_fence(__ATOMIC_RELEASE, "agent");
;             asm volatile("s_waitcnt vmcnt(0)" ::: "memory");
;             const unsigned og = xb_add(&bar[XB_TOP], 1u);
;             const unsigned tg = og / nx;
;             if (og + 1u == (tg + 1u) * nx) xb_add(&bar[XB_TOPGEN], 1u);
;             else XB_SPIN(xb_ld(&bar[XB_TOPGEN]) == tg, bar);
;             __builtin_amdgcn_fence(__ATOMIC_ACQUIRE, "agent");
;             xb_add(&bar[XB_XGEN(bx)], 1u);
;             asm volatile("s_waitcnt vmcnt(0)" ::: "memory");
.LBB0_475:
	s_andn2_saveexec_b64 s[10:11], s[10:11]
	s_cbranch_execz .LBB0_495
	s_mov_b64 s[10:11], exec
	v_mov_b32_e32 v1, 0x20208
	ds_read_b32 v1, v1
	s_waitcnt lgkmcnt(0)
	v_readfirstlane_b32 s101, v1
	s_nop 3
	s_cmp_lg_u32 s101, 0
	s_cbranch_scc1 .LBB0_492
	buffer_wbl2 sc1
	s_waitcnt lgkmcnt(0)
	s_waitcnt vmcnt(0)
	v_mbcnt_lo_u32_b32 v1, s10, 0
	v_mbcnt_hi_u32_b32 v1, s11, v1
	v_cmp_eq_u32_e32 vcc, 0, v1
	s_and_saveexec_b64 s[12:13], vcc
	s_cbranch_execz .LBB0_478
	s_bcnt1_i32_b64 s10, s[10:11]
	v_mov_b32_e32 v2, s10
	v_readlane_b32 s10, v254, 24
	v_readlane_b32 s11, v254, 25
	s_nop 4
	global_atomic_add v2, v157, v2, s[10:11] sc0
